# NA bias table reads as 8 ds_read2_b32 instead of 16 ds_read_b32
# speedup vs baseline: 1.0077x; 1.0054x over previous
; __device__ __forceinline__ void na_item(unsigned char* smem, const bf16_t* U, const float* rpb_l, bf16_t* O, int b, int rp, int hp, float shift) {
;     ...
;         const int relA = rsA + i - rA + 7, relB = relA - 1;
;         const int brA = min(max(relA, 0), 14), brB = min(max(relB, 0), 14);
; #pragma unroll
;         for (int g = 0; g < 2; ++g)
; #pragma unroll
;             for (int j = 0; j < 4; ++j) {
;                 const int kc = kcol0 + 16 * g + 4 * fq + j;
;                 const bool valid = (kc >= cs) && (kc < cs + 16);
;                 const int idx = min(max(kc - qc + 15, 0), 30);
;                 sA[g][j] = (valid && latA) ? sA[g][j] + bias[(hh * 15 + brA) * 32 + idx] : -INFINITY;
;                 sB[g][j] = (valid && latB) ? sB[g][j] + bias[(hh * 15 + brB) * 32 + idx] : -INFINITY;
;             }
.LBB0_859:
	s_bitcmp1_b32 s78, 0
	s_cselect_b32 s18, 0xd800, 0
	v_add_u32_e32 v111, s18, v121
	v_add_u32_e32 v86, v111, v108
	v_add_u32_e32 v144, v86, v126
	ds_read_b128 v[164:167], v144 offset:2304
	ds_read_b128 v[168:171], v144
	v_mov_b64_e32 v[80:81], s[62:63]
	v_mov_b64_e32 v[78:79], s[60:61]
	v_add_u32_e32 v145, v86, v127
	ds_read_b128 v[172:175], v145 offset:18432
	ds_read_b128 v[176:179], v145 offset:20736
	ds_read_b128 v[200:203], v144 offset:64
	ds_read_b128 v[204:207], v145 offset:18496
	s_cmp_lt_u32 s78, 8
	s_cselect_b64 vcc, -1, 0
	s_add_i32 s79, s97, s78
	ds_read_b128 v[212:215], v144 offset:2368
	s_waitcnt lgkmcnt(6)
	v_mfma_f32_16x16x32_bf16 v[136:139], v[164:167], v[14:17], v[78:81]
	s_max_i32 s18, s79, -7
	s_add_i32 s18, s18, 7
	s_min_u32 s18, s18, 14
	v_mfma_f32_16x16x32_bf16 v[140:143], v[164:167], v[22:25], v[78:81]
	ds_read_b128 v[164:167], v145 offset:20800
	s_waitcnt lgkmcnt(6)
	v_mfma_f32_16x16x32_bf16 v[82:85], v[168:171], v[14:17], v[78:81]
	v_mfma_f32_16x16x32_bf16 v[74:77], v[168:171], v[22:25], v[78:81]
	s_waitcnt lgkmcnt(5)
	v_mfma_f32_16x16x32_bf16 v[90:93], v[172:175], v[14:17], v[78:81]
	v_mfma_f32_16x16x32_bf16 v[86:89], v[172:175], v[22:25], v[78:81]
	s_waitcnt lgkmcnt(4)
	v_mfma_f32_16x16x32_bf16 v[156:159], v[176:179], v[14:17], v[78:81]
	v_mfma_f32_16x16x32_bf16 v[160:163], v[176:179], v[22:25], v[78:81]
	s_nop 2
	s_waitcnt lgkmcnt(3)
	v_mfma_f32_16x16x32_bf16 v[102:105], v[200:203], v[18:21], v[82:85]
	s_nop 2
	v_mfma_f32_16x16x32_bf16 v[98:101], v[200:203], v[26:29], v[74:77]
	s_waitcnt lgkmcnt(2)
	v_mfma_f32_16x16x32_bf16 v[74:77], v[204:207], v[18:21], v[90:93]
	v_mfma_f32_16x16x32_bf16 v[78:81], v[204:207], v[26:29], v[86:89]
	s_nop 2
	s_waitcnt lgkmcnt(1)
	v_mfma_f32_16x16x32_bf16 v[94:97], v[212:215], v[18:21], v[136:139]
	v_mfma_f32_16x16x32_bf16 v[90:93], v[212:215], v[26:29], v[140:143]
	s_nop 1
	v_add_u32_e32 v136, s18, v122
	v_lshl_add_u32 v138, v136, 7, s4
	v_add_u32_e32 v229, v138, v228
	s_waitcnt lgkmcnt(0)
	v_mfma_f32_16x16x32_bf16 v[82:85], v[164:167], v[18:21], v[156:159]
	s_cmp_ge_i32 s78, s5
	s_cselect_b64 s[76:77], -1, 0
	s_max_i32 s18, s79, -6
	s_add_i32 s18, s18, 6
	s_min_u32 s18, s18, 14
	v_mfma_f32_16x16x32_bf16 v[86:89], v[164:167], v[26:29], v[160:163]
	v_add_u32_e32 v139, s18, v122
	v_lshl_add_u32 v139, v139, 7, s4
	v_add_u32_e32 v230, v139, v228
	ds_read2_b32 v[180:181], v229 offset1:1
	ds_read2_b32 v[188:189], v230 offset1:1
	ds_read2_b32 v[182:183], v229 offset0:2 offset1:3
	ds_read2_b32 v[190:191], v230 offset0:2 offset1:3
	ds_read2_b32 v[184:185], v229 offset0:16 offset1:17
	ds_read2_b32 v[192:193], v230 offset0:16 offset1:17
	ds_read2_b32 v[186:187], v229 offset0:18 offset1:19
	ds_read2_b32 v[194:195], v230 offset0:18 offset1:19
	s_waitcnt lgkmcnt(6)
	s_and_b64 s[18:19], s[20:21], vcc
	v_add_f32_e32 v180, v102, v180
	v_cndmask_b32_e64 v137, v154, v180, s[18:19]
	s_and_b64 s[18:19], s[20:21], s[76:77]
	v_add_f32_e32 v188, v98, v188
	v_cndmask_b32_e64 v136, v154, v188, s[18:19]
	s_and_b64 s[18:19], s[40:41], vcc
	v_add_f32_e32 v181, v103, v181
	v_cndmask_b32_e64 v102, v154, v181, s[18:19]
	s_and_b64 s[18:19], s[40:41], s[76:77]
	v_add_f32_e32 v189, v99, v189
	v_cndmask_b32_e64 v98, v154, v189, s[18:19]
	s_waitcnt lgkmcnt(4)
	s_and_b64 s[18:19], s[16:17], vcc
	v_add_f32_e32 v182, v104, v182
	v_cndmask_b32_e64 v103, v154, v182, s[18:19]
	s_and_b64 s[18:19], s[16:17], s[76:77]
	v_add_f32_e32 v190, v100, v190
	v_cndmask_b32_e64 v99, v154, v190, s[18:19]
	s_and_b64 s[18:19], s[2:3], vcc
	v_add_f32_e32 v183, v105, v183
	v_cndmask_b32_e64 v104, v154, v183, s[18:19]
	s_and_b64 s[18:19], s[2:3], s[76:77]
	v_add_f32_e32 v191, v101, v191
	v_cndmask_b32_e64 v100, v154, v191, s[18:19]
	s_waitcnt lgkmcnt(2)
	s_and_b64 s[18:19], s[26:27], vcc
	v_add_f32_e32 v184, v94, v184
	v_cndmask_b32_e64 v105, v154, v184, s[18:19]
	s_and_b64 s[18:19], s[26:27], s[76:77]
	v_add_f32_e32 v192, v90, v192
	v_cndmask_b32_e64 v101, v154, v192, s[18:19]
	s_and_b64 s[18:19], s[74:75], vcc
	v_add_f32_e32 v185, v95, v185
	v_cndmask_b32_e64 v140, v154, v185, s[18:19]
	s_and_b64 s[18:19], s[74:75], s[76:77]
	v_add_f32_e32 v193, v91, v193
	v_cndmask_b32_e64 v94, v154, v193, s[18:19]
	s_waitcnt lgkmcnt(0)
; #define LASP __attribute__((address_space(3)))
; __device__ __forceinline__ void na_item(unsigned char* smem, const bf16_t* U, const float* rpb_l, bf16_t* O, int b, int rp, int hp, float shift) {
;     ...
;                 sA[g][j] = (valid && latA) ? sA[g][j] + bias[(hh * 15 + brA) * 32 + idx] : -INFINITY;
;                 sB[g][j] = (valid && latB) ? sB[g][j] + bias[(hh * 15 + brB) * 32 + idx] : -INFINITY;
;             }
;         if (!hasctx) {
; #pragma unroll
;             for (int g = 2; g < 4; ++g) { sA[g] = (f32x4_t){-INFINITY, -INFINITY, -INFINITY, -INFINITY}; sB[g] = sA[g]; }
;         }
;         { float psA = 0.f, psB = 0.f;
; #pragma unroll
;           for (int g = 0; g < 4; ++g)
; #pragma unroll
;               for (int j = 0; j < 4; ++j) { const float pa = __builtin_amdgcn_exp2f(sA[g][j]); sA[g][j] = pa; psA += pa;
;                                             const float pb_ = __builtin_amdgcn_exp2f(sB[g][j]); sB[g][j] = pb_; psB += pb_; }
;           lA += psA; lB += psB; }
; #pragma unroll
;         for (int kp = 0; kp < 2; ++kp) {
;             u32x4_t pk;
;             pk.x = pg8::cvt_pk_bf16(sA[2 * kp][0], sA[2 * kp][1]); pk.y = pg8::cvt_pk_bf16(sA[2 * kp][2], sA[2 * kp][3]); pk.z = pg8::cvt_pk_bf16(sA[2 * kp + 1][0], sA[2 * kp + 1][1]); pk.w = pg8::cvt_pk_bf16(sA[2 * kp + 1][2], sA[2 * kp + 1][3]);
;             const bf16x8_t pbA = __builtin_bit_cast(bf16x8_t, pk);
;             pk.x = pg8::cvt_pk_bf16(sB[2 * kp][0], sB[2 * kp][1]); pk.y = pg8::cvt_pk_bf16(sB[2 * kp][2], sB[2 * kp][3]); pk.z = pg8::cvt_pk_bf16(sB[2 * kp + 1][0], sB[2 * kp + 1][1]); pk.w = pg8::cvt_pk_bf16(sB[2 * kp + 1][2], sB[2 * kp + 1][3]);
;             const bf16x8_t pbB = __builtin_bit_cast(bf16x8_t, pk);
;             LASP unsigned char* vb = kp == 0 ? base + O_VL + (kcol0 + 4 * fq + (fr >> 2)) * KR : base + O_VC + (4 * fq + (fr >> 2)) * KR;
; #pragma unroll
;             for (int dg = 0; dg < 4; ++dg) {
;                 LASP unsigned char* va = vb + (16 * dg + 4 * (fr & 3)) * 2;
;                 const s16x4 v0 = __builtin_amdgcn_ds_read_tr16_b64_v4i16((LASP s16x4*)va);
;                 const s16x4 v1 = __builtin_amdgcn_ds_read_tr16_b64_v4i16((LASP s16x4*)(va + 16 * KR));
;                 const bf16x8_t vf = __builtin_shufflevector(v0, v1, 0, 1, 2, 3, 4, 5, 6, 7);
;                 oA[dg] = __builtin_amdgcn_mfma_f32_16x16x32_bf16(vf, pbA, oA[dg], 0, 0, 0);
	s_and_b64 s[18:19], s[52:53], vcc
	v_add_f32_e32 v186, v96, v186
	v_cndmask_b32_e64 v91, v154, v186, s[18:19]
	s_and_b64 s[18:19], s[52:53], s[76:77]
	v_add_f32_e32 v194, v92, v194
	v_cndmask_b32_e64 v90, v154, v194, s[18:19]
	s_and_b64 s[18:19], s[38:39], vcc
	v_add_f32_e32 v187, v97, v187
	v_cndmask_b32_e64 v96, v154, v187, s[18:19]
	s_and_b64 s[18:19], s[38:39], s[76:77]
	v_add_f32_e32 v195, v93, v195
	v_cndmask_b32_e64 v92, v154, v195, s[18:19]
	s_mov_b64 s[76:77], exec
	s_mov_b64 s[78:79], exec
	v_add3_u32 v198, v111, v125, v123
	ds_read_b64_tr_b16 v[166:167], v198 offset:11520
	ds_read_b64_tr_b16 v[164:165], v198 offset:9216
	ds_read_b64_tr_b16 v[168:169], v198 offset:9280
	ds_read_b64_tr_b16 v[170:171], v198 offset:11584
	ds_read_b64_tr_b16 v[172:173], v198 offset:9248
	ds_read_b64_tr_b16 v[174:175], v198 offset:11552
	ds_read_b64_tr_b16 v[176:177], v198 offset:9312
	ds_read_b64_tr_b16 v[178:179], v198 offset:11616
	v_add3_u32 v199, v111, v124, v123
	ds_read_b64_tr_b16 v[182:183], v199 offset:25344
	ds_read_b64_tr_b16 v[180:181], v199 offset:23040
	ds_read_b64_tr_b16 v[184:185], v199 offset:23104
	ds_read_b64_tr_b16 v[186:187], v199 offset:25408
	v_exp_f32_e32 v137, v137
	v_exp_f32_e32 v136, v136
	v_exp_f32_e32 v139, v102
	v_exp_f32_e32 v138, v98
	v_exp_f32_e32 v103, v103
	v_exp_f32_e32 v102, v99
	v_exp_f32_e32 v143, v104
	v_exp_f32_e32 v142, v100
	v_cndmask_b32_e32 v148, v154, v84, vcc
	v_cndmask_b32_e32 v149, v154, v83, vcc
	v_cndmask_b32_e32 v83, v154, v75, vcc
	v_cndmask_b32_e32 v84, v154, v74, vcc
	v_exp_f32_e32 v105, v105
	v_exp_f32_e32 v104, v101
	v_exp_f32_e32 v141, v140
	v_exp_f32_e32 v140, v94
	v_pk_add_f32 v[74:75], v[136:137], 0 op_sel_hi:[1,0]
	v_exp_f32_e32 v95, v91
	v_pk_add_f32 v[74:75], v[138:139], v[74:75]
	v_exp_f32_e32 v94, v90
	v_pk_add_f32 v[74:75], v[102:103], v[74:75]
	v_exp_f32_e32 v93, v96
	v_pk_add_f32 v[74:75], v[142:143], v[74:75]
	v_exp_f32_e32 v92, v92
	v_pk_add_f32 v[74:75], v[104:105], v[74:75]
	v_cvt_pk_bf16_f32 v101, v102, v142
	v_cvt_pk_bf16_f32 v102, v104, v140
	v_pk_add_f32 v[74:75], v[140:141], v[74:75]
	v_cvt_pk_bf16_f32 v96, v137, v139
	v_cvt_pk_bf16_f32 v98, v105, v141
	v_cvt_pk_bf16_f32 v100, v136, v138
	v_cndmask_b32_e32 v97, v154, v89, vcc
	v_cndmask_b32_e32 v76, v154, v76, vcc
	v_cndmask_b32_e32 v145, v154, v87, vcc
	v_exp_f32_e32 v87, v76
	v_exp_f32_e32 v76, v97
	v_cvt_pk_bf16_f32 v97, v103, v143
	v_cvt_pk_bf16_f32 v99, v95, v93
	v_cvt_pk_bf16_f32 v103, v94, v92
	ds_read_b64_tr_b16 v[188:189], v199 offset:23072
	ds_read_b64_tr_b16 v[190:191], v199 offset:25376
	s_waitcnt lgkmcnt(12)
	v_mfma_f32_16x16x32_bf16 v[70:73], v[164:167], v[96:99], v[70:73]
	v_cndmask_b32_e32 v144, v154, v88, vcc
	v_cndmask_b32_e32 v146, v154, v86, vcc
	v_cndmask_b32_e32 v81, v154, v81, vcc
	v_mfma_f32_16x16x32_bf16 v[54:57], v[164:167], v[100:103], v[54:57]
	v_cndmask_b32_e32 v80, v154, v80, vcc
	v_cndmask_b32_e32 v79, v154, v79, vcc
	ds_read_b64_tr_b16 v[164:165], v199 offset:23136
	ds_read_b64_tr_b16 v[166:167], v199 offset:25440
	s_waitcnt lgkmcnt(12)
	v_mfma_f32_16x16x32_bf16 v[62:65], v[168:171], v[96:99], v[62:65]
	v_cndmask_b32_e32 v78, v154, v78, vcc
	v_cndmask_b32_e32 v147, v154, v85, vcc
	v_cndmask_b32_e32 v82, v154, v82, vcc
	v_mfma_f32_16x16x32_bf16 v[6:9], v[168:171], v[100:103], v[6:9]
	v_cndmask_b32_e32 v77, v154, v77, vcc
	v_exp_f32_e32 v91, v84
	v_exp_f32_e32 v90, v78
	v_exp_f32_e32 v89, v83
	v_exp_f32_e32 v88, v79
	v_exp_f32_e32 v86, v80
	v_exp_f32_e32 v85, v77
	v_exp_f32_e32 v84, v81
	v_exp_f32_e32 v83, v82
	v_exp_f32_e32 v82, v146
	v_exp_f32_e32 v81, v149
	v_exp_f32_e32 v80, v145
	v_exp_f32_e32 v79, v148
	v_exp_f32_e32 v78, v144
	v_exp_f32_e32 v77, v147
	s_waitcnt lgkmcnt(10)
	v_mfma_f32_16x16x32_bf16 v[66:69], v[172:175], v[96:99], v[66:69]
	v_add_f32_e64 v74, v94, v74
	v_add_f32_e64 v75, v95, v75
	v_lshl_add_u64 v[114:115], v[114:115], 0, s[14:15]
	v_pk_add_f32 v[74:75], v[92:93], v[74:75]
	v_mfma_f32_16x16x32_bf16 v[2:5], v[172:175], v[100:103], v[2:5]
	v_add_f32_e64 v74, v90, v74
	v_add_f32_e64 v75, v91, v75
	v_lshl_add_u64 v[116:117], v[116:117], 0, s[34:35]
	v_pk_add_f32 v[74:75], v[88:89], v[74:75]
	s_waitcnt lgkmcnt(8)
	v_mfma_f32_16x16x32_bf16 v[58:61], v[176:179], v[96:99], v[58:61]
	v_cvt_pk_bf16_f32 v96, v91, v89
	v_cvt_pk_bf16_f32 v97, v87, v85
	v_cvt_pk_bf16_f32 v98, v83, v81
	v_mfma_f32_16x16x32_bf16 v[10:13], v[176:179], v[100:103], v[10:13]
	v_cvt_pk_bf16_f32 v99, v79, v77
	v_cvt_pk_bf16_f32 v100, v90, v88
	v_cvt_pk_bf16_f32 v101, v86, v84
	v_cvt_pk_bf16_f32 v102, v82, v80
	v_cvt_pk_bf16_f32 v103, v78, v76
	s_waitcnt lgkmcnt(6)
	v_mfma_f32_16x16x32_bf16 v[70:73], v[180:183], v[96:99], v[70:73]
	v_pk_add_f32 v[74:75], v[86:87], v[74:75]
	s_andn2_b64 vcc, exec, s[28:29]
	v_mfma_f32_16x16x32_bf16 v[54:57], v[180:183], v[100:103], v[54:57]
	v_pk_add_f32 v[74:75], v[84:85], v[74:75]
	s_waitcnt lgkmcnt(4)
	v_mfma_f32_16x16x32_bf16 v[62:65], v[184:187], v[96:99], v[62:65]
	v_add_f32_e64 v74, v82, v74
	v_add_f32_e64 v75, v83, v75
	v_pk_add_f32 v[74:75], v[80:81], v[74:75]
	v_mfma_f32_16x16x32_bf16 v[6:9], v[184:187], v[100:103], v[6:9]
	v_pk_add_f32 v[74:75], v[78:79], v[74:75]
	s_waitcnt lgkmcnt(2)
	v_mfma_f32_16x16x32_bf16 v[66:69], v[188:191], v[96:99], v[66:69]
	v_add_f32_e64 v74, v76, v74
	v_add_f32_e64 v75, v77, v75
	s_waitcnt lgkmcnt(0)
	s_barrier
	v_pk_add_f32 v[112:113], v[112:113], v[74:75]
	v_mfma_f32_16x16x32_bf16 v[2:5], v[188:191], v[100:103], v[2:5]
	v_mfma_f32_16x16x32_bf16 v[58:61], v[164:167], v[96:99], v[58:61]
	v_mfma_f32_16x16x32_bf16 v[10:13], v[164:167], v[100:103], v[10:13]
	s_cbranch_vccz .LBB0_819
	s_mov_b32 s78, s54
	s_branch .LBB0_848
